# weight-conversion tiles: the 16 per-thread tile loads are issued together with one counted drain instead of two loads per loop trip with a wait each (prologue de-serialisation)
# speedup vs baseline: 1.0021x; 1.0004x over previous
.LBB0_301:
	v_ashrrev_i32_e32 v3, 6, v2
	v_add_u32_e32 v12, s3, v3
	v_ashrrev_i32_e32 v13, 31, v12
	v_lshlrev_b64 v[12:13], 12, v[12:13]
	v_lshl_add_u64 v[12:13], v[4:5], 0, v[12:13]
	s_mov_b64 s[14:15], 0x4000
	v_mad_u32_u24 v14, v3, s13, v0
	global_load_dword v18, v[12:13], off
	v_lshl_add_u64 v[12:13], v[12:13], 0, s[14:15]
	global_load_dword v19, v[12:13], off
	v_lshl_add_u64 v[12:13], v[12:13], 0, s[14:15]
	global_load_dword v20, v[12:13], off
	v_lshl_add_u64 v[12:13], v[12:13], 0, s[14:15]
	global_load_dword v21, v[12:13], off
	v_lshl_add_u64 v[12:13], v[12:13], 0, s[14:15]
	global_load_dword v22, v[12:13], off
	v_lshl_add_u64 v[12:13], v[12:13], 0, s[14:15]
	global_load_dword v23, v[12:13], off
	v_lshl_add_u64 v[12:13], v[12:13], 0, s[14:15]
	global_load_dword v24, v[12:13], off
	v_lshl_add_u64 v[12:13], v[12:13], 0, s[14:15]
	global_load_dword v25, v[12:13], off
	v_lshl_add_u64 v[12:13], v[12:13], 0, s[14:15]
	global_load_dword v26, v[12:13], off
	v_lshl_add_u64 v[12:13], v[12:13], 0, s[14:15]
	global_load_dword v27, v[12:13], off
	v_lshl_add_u64 v[12:13], v[12:13], 0, s[14:15]
	global_load_dword v28, v[12:13], off
	v_lshl_add_u64 v[12:13], v[12:13], 0, s[14:15]
	global_load_dword v29, v[12:13], off
	v_lshl_add_u64 v[12:13], v[12:13], 0, s[14:15]
	global_load_dword v30, v[12:13], off
	v_lshl_add_u64 v[12:13], v[12:13], 0, s[14:15]
	global_load_dword v31, v[12:13], off
	v_lshl_add_u64 v[12:13], v[12:13], 0, s[14:15]
	global_load_dword v32, v[12:13], off
	v_lshl_add_u64 v[12:13], v[12:13], 0, s[14:15]
	global_load_dword v33, v[12:13], off
	s_waitcnt vmcnt(15)
	ds_write_b32 v14, v18
	s_waitcnt vmcnt(14)
	ds_write_b32 v14, v19 offset:1040
	s_waitcnt vmcnt(13)
	ds_write_b32 v14, v20 offset:2080
	s_waitcnt vmcnt(12)
	ds_write_b32 v14, v21 offset:3120
	s_waitcnt vmcnt(11)
	ds_write_b32 v14, v22 offset:4160
	s_waitcnt vmcnt(10)
	ds_write_b32 v14, v23 offset:5200
	s_waitcnt vmcnt(9)
	ds_write_b32 v14, v24 offset:6240
	s_waitcnt vmcnt(8)
	ds_write_b32 v14, v25 offset:7280
	s_waitcnt vmcnt(7)
	ds_write_b32 v14, v26 offset:8320
	s_waitcnt vmcnt(6)
	ds_write_b32 v14, v27 offset:9360
	s_waitcnt vmcnt(5)
	ds_write_b32 v14, v28 offset:10400
	s_waitcnt vmcnt(4)
	ds_write_b32 v14, v29 offset:11440
	s_waitcnt vmcnt(3)
	ds_write_b32 v14, v30 offset:12480
	s_waitcnt vmcnt(2)
	ds_write_b32 v14, v31 offset:13520
	s_waitcnt vmcnt(1)
	ds_write_b32 v14, v32 offset:14560
	s_waitcnt vmcnt(0)
	ds_write_b32 v14, v33 offset:15600
	s_mov_b64 s[38:39], exec
	s_or_b64 exec, exec, s[38:39]
	v_cmp_ne_u32_e32 vcc, v8, v9
	v_lshl_add_u32 v3, v9, 8, v2
	s_orn2_b64 s[22:23], vcc, exec

.LBB0_390:
	v_ashrrev_i32_e32 v3, 6, v2
	v_add_u32_e32 v12, s36, v3
	v_mad_i64_i32 v[12:13], s[12:13], v12, s24, v[4:5]
	s_mov_b64 s[14:15], 0x20c00
	v_mad_u32_u24 v14, v3, s21, v0
	global_load_dword v18, v[12:13], off
	v_lshl_add_u64 v[12:13], v[12:13], 0, s[14:15]
	global_load_dword v19, v[12:13], off
	v_lshl_add_u64 v[12:13], v[12:13], 0, s[14:15]
	global_load_dword v20, v[12:13], off
	v_lshl_add_u64 v[12:13], v[12:13], 0, s[14:15]
	global_load_dword v21, v[12:13], off
	v_lshl_add_u64 v[12:13], v[12:13], 0, s[14:15]
	global_load_dword v22, v[12:13], off
	v_lshl_add_u64 v[12:13], v[12:13], 0, s[14:15]
	global_load_dword v23, v[12:13], off
	v_lshl_add_u64 v[12:13], v[12:13], 0, s[14:15]
	global_load_dword v24, v[12:13], off
	v_lshl_add_u64 v[12:13], v[12:13], 0, s[14:15]
	global_load_dword v25, v[12:13], off
	v_lshl_add_u64 v[12:13], v[12:13], 0, s[14:15]
	global_load_dword v26, v[12:13], off
	v_lshl_add_u64 v[12:13], v[12:13], 0, s[14:15]
	global_load_dword v27, v[12:13], off
	v_lshl_add_u64 v[12:13], v[12:13], 0, s[14:15]
	global_load_dword v28, v[12:13], off
	v_lshl_add_u64 v[12:13], v[12:13], 0, s[14:15]
	global_load_dword v29, v[12:13], off
	v_lshl_add_u64 v[12:13], v[12:13], 0, s[14:15]
	global_load_dword v30, v[12:13], off
	v_lshl_add_u64 v[12:13], v[12:13], 0, s[14:15]
	global_load_dword v31, v[12:13], off
	v_lshl_add_u64 v[12:13], v[12:13], 0, s[14:15]
	global_load_dword v32, v[12:13], off
	v_lshl_add_u64 v[12:13], v[12:13], 0, s[14:15]
	global_load_dword v33, v[12:13], off
	s_waitcnt vmcnt(15)
	ds_write_b32 v14, v18
	s_waitcnt vmcnt(14)
	ds_write_b32 v14, v19 offset:1040
	s_waitcnt vmcnt(13)
	ds_write_b32 v14, v20 offset:2080
	s_waitcnt vmcnt(12)
	ds_write_b32 v14, v21 offset:3120
	s_waitcnt vmcnt(11)
	ds_write_b32 v14, v22 offset:4160
	s_waitcnt vmcnt(10)
	ds_write_b32 v14, v23 offset:5200
	s_waitcnt vmcnt(9)
	ds_write_b32 v14, v24 offset:6240
	s_waitcnt vmcnt(8)
	ds_write_b32 v14, v25 offset:7280
	s_waitcnt vmcnt(7)
	ds_write_b32 v14, v26 offset:8320
	s_waitcnt vmcnt(6)
	ds_write_b32 v14, v27 offset:9360
	s_waitcnt vmcnt(5)
	ds_write_b32 v14, v28 offset:10400
	s_waitcnt vmcnt(4)
	ds_write_b32 v14, v29 offset:11440
	s_waitcnt vmcnt(3)
	ds_write_b32 v14, v30 offset:12480
	s_waitcnt vmcnt(2)
	ds_write_b32 v14, v31 offset:13520
	s_waitcnt vmcnt(1)
	ds_write_b32 v14, v32 offset:14560
	s_waitcnt vmcnt(0)
	ds_write_b32 v14, v33 offset:15600
	s_mov_b64 s[22:23], exec
	s_or_b64 exec, exec, s[22:23]
	v_cmp_ne_u32_e32 vcc, v8, v9
	v_lshl_add_u32 v3, v9, 8, v2
	s_orn2_b64 s[22:23], vcc, exec
